# first grid barrier: XCD census poll keeps its 16 counter loads in flight together instead of load-wait-add one at a time
# speedup vs baseline: 1.0037x; 1.0037x over previous
.LBB0_25:
	s_mov_b64 s[22:23], -1
	s_waitcnt lgkmcnt(0)
	global_load_dword v0, v1, s[80:81] sc1
	v_readlane_b32 s20, v253, 13
	v_readlane_b32 s21, v253, 14
	s_nop 4
	global_load_dword v2, v1, s[20:21] sc1
	v_readlane_b32 s20, v253, 15
	v_readlane_b32 s21, v253, 16
	s_nop 4
	global_load_dword v3, v1, s[20:21] sc1
	v_readlane_b32 s20, v253, 17
	v_readlane_b32 s21, v253, 18
	s_nop 4
	global_load_dword v4, v1, s[20:21] sc1
	v_readlane_b32 s20, v253, 19
	v_readlane_b32 s21, v253, 20
	s_nop 4
	global_load_dword v5, v1, s[20:21] sc1
	v_readlane_b32 s20, v253, 21
	v_readlane_b32 s21, v253, 22
	s_nop 4
	global_load_dword v6, v1, s[20:21] sc1
	v_readlane_b32 s20, v253, 23
	v_readlane_b32 s21, v253, 24
	s_nop 4
	global_load_dword v7, v1, s[20:21] sc1
	v_readlane_b32 s20, v253, 25
	v_readlane_b32 s21, v253, 26
	s_nop 4
	global_load_dword v8, v1, s[20:21] sc1
	v_readlane_b32 s20, v253, 27
	v_readlane_b32 s21, v253, 28
	s_nop 4
	global_load_dword v9, v1, s[20:21] sc1
	v_readlane_b32 s20, v253, 29
	v_readlane_b32 s21, v253, 30
	s_nop 4
	global_load_dword v10, v1, s[20:21] sc1
	v_readlane_b32 s20, v253, 31
	v_readlane_b32 s21, v253, 32
	s_nop 4
	global_load_dword v11, v1, s[20:21] sc1
	v_readlane_b32 s20, v253, 33
	v_readlane_b32 s21, v253, 34
	s_nop 4
	global_load_dword v12, v1, s[20:21] sc1
	v_readlane_b32 s20, v253, 35
	v_readlane_b32 s21, v253, 36
	s_nop 4
	global_load_dword v13, v1, s[20:21] sc1
	v_readlane_b32 s20, v253, 37
	v_readlane_b32 s21, v253, 38
	s_nop 4
	global_load_dword v14, v1, s[20:21] sc1
	v_readlane_b32 s20, v253, 39
	v_readlane_b32 s21, v253, 40
	s_nop 4
	global_load_dword v15, v1, s[20:21] sc1
	v_readlane_b32 s20, v253, 41
	v_readlane_b32 s21, v253, 42
	s_nop 4
	global_load_dword v16, v1, s[20:21] sc1
	s_mov_b64 s[20:21], -1
	s_waitcnt vmcnt(0)
	v_add_u32_e32 v17, v2, v0
	v_add_u32_e32 v17, v17, v3
	v_add_u32_e32 v17, v17, v4
	v_add_u32_e32 v17, v17, v5
	v_add_u32_e32 v17, v17, v6
	v_add_u32_e32 v17, v17, v7
	v_add_u32_e32 v17, v17, v8
	v_add_u32_e32 v17, v17, v9
	v_add_u32_e32 v17, v17, v10
	v_add_u32_e32 v17, v17, v11
	v_add_u32_e32 v17, v17, v12
	v_add_u32_e32 v17, v17, v13
	v_add_u32_e32 v17, v17, v14
	v_add_u32_e32 v17, v17, v15
	v_add_u32_e32 v17, v17, v16
	v_cmp_eq_u32_e32 vcc, s68, v17
	s_cbranch_vccnz .LBB0_24
	s_and_b32 s17, s8, 0xff
	s_cmp_eq_u32 s17, 0
	s_mov_b64 s[24:25], -1
	s_sleep 1
	s_cbranch_scc1 .LBB0_29
	s_and_b64 vcc, exec, s[24:25]
	s_cbranch_vccz .LBB0_24
